# baseline (speedup 1.0000x reference)
; __device__ __forceinline__ void run_phase(const Params& p, int ph) {
;     ...
;   } else if (ph == 4 || ph == 13 || ph == 18 || ph == 27) {
;     const bf16_t* delta = (ph == 4 || ph == 18) ? outb : fb;
;     const float* gain = ph == 4 ? p.in[5] : ph == 13 ? p.in[7] : ph == 18 ? p.in[5] + 1024 : p.in[7] + 1024;
;     const int reps = (p.dup & 16) ? 2 : 1;
;     for (int rep = 0; rep < reps; ++rep) if (EN(128)) phase_norm(p, 0, delta, gain, ph == 27, rep + 1 < reps);
.LBB0_1279:
	s_add_u32 s8, s14, 0x139a6000
	s_addc_u32 s9, s15, 0
	s_or_b64 s[4:5], s[6:7], s[4:5]
	s_and_b64 s[4:5], s[4:5], exec
	s_load_dwordx4 s[4:7], s[72:73], 0xe8
	s_mov_b32 s28, 0
	s_waitcnt lgkmcnt(0)
	s_cselect_b32 s9, s7, s9
	s_cselect_b32 s8, s6, s8
	s_cmp_lg_u32 s34, 27
	s_cselect_b64 s[10:11], -1, 0
	s_mov_b32 s29, 1
	s_add_u32 s12, s14, 0x61a6000
	s_addc_u32 s13, s15, 0
	s_add_u32 s16, s6, 0x800
	s_addc_u32 s17, s7, 0
	s_add_u32 s18, s14, 0x3be6000
	s_addc_u32 s19, s15, 0
	s_branch .LBB0_1281

; __device__ void phase_norm(const Params& p, int src_is_input, const bf16_t* delta, const float* gain, int final_out, int dry) {
;     ...
;   const int stride = gridDim.x * 8;
;   int row = blockIdx.x * 8 + wid;
;   uint4 dn[2], xn[2];
;     ...
;   if (row < T_TOK) NORM_FETCH(row);
;   float gq[16];
; #pragma unroll
;   for (int i = 0; i < 2; ++i) {
;     const float4 a = *(const float4*)(gain + i * 512 + lane * 8), b = *(const float4*)(gain + i * 512 + lane * 8 + 4);
;     gq[i * 8 + 0] = a.x; gq[i * 8 + 1] = a.y; gq[i * 8 + 2] = a.z; gq[i * 8 + 3] = a.w;
;     gq[i * 8 + 4] = b.x; gq[i * 8 + 5] = b.y; gq[i * 8 + 6] = b.z; gq[i * 8 + 7] = b.w;
;   }
;   while (row < T_TOK) {
.LBB0_1283:
	s_or_b64 exec, exec, s[4:5]
	s_add_i32 s28, s28, 1
	s_and_saveexec_b64 s[20:21], vcc
	s_cbranch_execz .LBB0_1280
	v_lshlrev_b64 v[20:21], 2, v[0:1]
	v_lshl_add_u64 v[14:15], s[2:3], 0, v[20:21]
	global_load_dwordx4 v[2:5], v[14:15], off offset:16
	global_load_dwordx4 v[6:9], v[14:15], off
	global_load_dwordx4 v[10:13], v[14:15], off offset:2064
	s_nop 0
	global_load_dwordx4 v[14:17], v[14:15], off offset:2048
	v_and_b32_e32 v22, 64, v228
	v_add_u32_e32 v22, 64, v22
	v_xor_b32_e32 v23, 32, v228
	v_cmp_lt_i32_e32 vcc, v23, v22
	v_readlane_b32 s6, v254, 10
	v_cmp_eq_u32_e64 s[4:5], 0, v19
	v_cndmask_b32_e32 v23, v228, v23, vcc
	v_lshlrev_b32_e32 v66, 2, v23
	v_xor_b32_e32 v23, 16, v228
	v_cmp_lt_i32_e32 vcc, v23, v22
	v_add_u32_e32 v18, s6, v18
	v_ashrrev_i32_e32 v19, 31, v18
	v_cndmask_b32_e32 v23, v228, v23, vcc
	v_lshlrev_b32_e32 v67, 2, v23
	v_xor_b32_e32 v23, 8, v228
	v_cmp_lt_i32_e32 vcc, v23, v22
	s_cmp_ge_u32 s28, s29
	v_lshlrev_b64 v[18:19], 11, v[18:19]
	v_cndmask_b32_e32 v23, v228, v23, vcc
	v_lshlrev_b32_e32 v68, 2, v23
	v_xor_b32_e32 v23, 4, v228
	v_cmp_lt_i32_e32 vcc, v23, v22
	s_cselect_b64 s[22:23], -1, 0
	v_lshlrev_b64 v[52:53], 1, v[0:1]
	v_cndmask_b32_e32 v23, v228, v23, vcc
	v_lshlrev_b32_e32 v69, 2, v23
	v_xor_b32_e32 v23, 2, v228
	v_cmp_lt_i32_e32 vcc, v23, v22
	s_waitcnt vmcnt(7)
	v_lshl_add_u64 v[56:57], s[14:15], 0, v[18:19]
	v_lshl_add_u64 v[60:61], s[8:9], 0, v[18:19]
	v_cndmask_b32_e32 v23, v228, v23, vcc
	v_lshlrev_b32_e32 v70, 2, v23
	v_xor_b32_e32 v23, 1, v228
	v_cmp_lt_i32_e32 vcc, v23, v22
	v_lshl_add_u64 v[62:63], v[50:51], 2, s[18:19]
	s_mov_b64 s[24:25], 0
	v_cndmask_b32_e32 v22, v228, v23, vcc
	v_lshlrev_b32_e32 v71, 2, v22
	v_lshlrev_b64 v[22:23], 11, v[50:51]
	v_lshl_add_u64 v[54:55], s[14:15], 0, v[22:23]
	v_lshlrev_b64 v[22:23], 12, v[50:51]
	v_lshl_add_u64 v[20:21], v[22:23], 0, v[20:21]
	v_lshl_add_u64 v[58:59], s[16:17], 0, v[20:21]
	s_waitcnt vmcnt(0)
	s_branch .LBB0_1287

; __device__ __forceinline__ float lo2f(unsigned u) { return __uint_as_float(u << 16); }
; __device__ __forceinline__ float hi2f(unsigned u) { return __uint_as_float(u & 0xffff0000u); }
; __device__ void phase_norm(const Params& p, int src_is_input, const bf16_t* delta, const float* gain, int final_out, int dry) {
;     ...
;   while (row < T_TOK) {
;     float dv[16], xv[16];
;     float ss = 0.f;
; #pragma unroll
;     for (int i = 0; i < 2; ++i) {
;       const unsigned du[4] = {dn[i].x, dn[i].y, dn[i].z, dn[i].w}, xu[4] = {xn[i].x, xn[i].y, xn[i].z, xn[i].w};
; #pragma unroll
;       for (int j = 0; j < 4; ++j) {
;         dv[i * 8 + 2 * j] = lo2f(du[j]); dv[i * 8 + 2 * j + 1] = hi2f(du[j]);
;         xv[i * 8 + 2 * j] = lo2f(xu[j]); xv[i * 8 + 2 * j + 1] = hi2f(xu[j]);
;       }
;     }
; #pragma unroll
;     for (int j = 0; j < 16; ++j) ss += dv[j] * dv[j];
;     const int nrow = row + stride;
;     if (nrow < T_TOK) NORM_FETCH(nrow);
.LBB0_1286:
	s_waitcnt vmcnt(1)
	s_and_b64 s[6:7], exec, s[6:7]
	s_or_b64 s[24:25], s[6:7], s[24:25]
	v_readlane_b32 s6, v254, 15
	v_readlane_b32 s7, v254, 16
	v_readlane_b32 s26, v254, 17
	v_readlane_b32 s27, v254, 18
	v_lshl_add_u64 v[54:55], v[54:55], 0, s[6:7]
	v_lshl_add_u64 v[56:57], v[56:57], 0, s[6:7]
	v_lshl_add_u64 v[60:61], v[60:61], 0, s[6:7]
	v_readlane_b32 s6, v254, 21
	v_readlane_b32 s7, v254, 22
	v_lshl_add_u64 v[58:59], v[58:59], 0, s[26:27]
	v_mov_b64_e32 v[38:39], v[26:27]
	v_lshl_add_u64 v[62:63], v[62:63], 0, s[6:7]
	v_mov_b64_e32 v[40:41], v[28:29]
	v_mov_b64_e32 v[34:35], v[30:31]
	v_mov_b64_e32 v[36:37], v[32:33]
	v_mov_b64_e32 v[46:47], v[18:19]
	v_mov_b64_e32 v[48:49], v[20:21]
	v_mov_b64_e32 v[42:43], v[22:23]
	v_mov_b64_e32 v[44:45], v[24:25]
	s_andn2_b64 exec, exec, s[24:25]
	s_cbranch_execz .LBB0_1280

; __device__ __forceinline__ float lo2f(unsigned u) { return __uint_as_float(u << 16); }
; __device__ __forceinline__ float hi2f(unsigned u) { return __uint_as_float(u & 0xffff0000u); }
; __device__ void phase_norm(const Params& p, int src_is_input, const bf16_t* delta, const float* gain, int final_out, int dry) {
;     ...
;   while (row < T_TOK) {
;     float dv[16], xv[16];
;     float ss = 0.f;
; #pragma unroll
;     for (int i = 0; i < 2; ++i) {
;       const unsigned du[4] = {dn[i].x, dn[i].y, dn[i].z, dn[i].w}, xu[4] = {xn[i].x, xn[i].y, xn[i].z, xn[i].w};
; #pragma unroll
;       for (int j = 0; j < 4; ++j) {
;         dv[i * 8 + 2 * j] = lo2f(du[j]); dv[i * 8 + 2 * j + 1] = hi2f(du[j]);
;         xv[i * 8 + 2 * j] = lo2f(xu[j]); xv[i * 8 + 2 * j + 1] = hi2f(xu[j]);
;       }
;     }
; #pragma unroll
;     for (int j = 0; j < 16; ++j) ss += dv[j] * dv[j];
;     const int nrow = row + stride;
;     if (nrow < T_TOK) NORM_FETCH(nrow);
;     ss = wave_sum(ss);
;     const float rr = rsqrtf(ss * (1.f / 1024.f) + 1e-6f);
;     float y[16];
;     float ss2 = 0.f;
; #pragma unroll
;     for (int j = 0; j < 16; ++j) { y[j] = xv[j] + dv[j] * rr * gq[j]; ss2 += y[j] * y[j]; }
;     if (!dry) {
; #pragma unroll
;       for (int i = 0; i < 2; ++i) {
;         if (final_out) {
;           float* op = p.out + (size_t)row * DM + i * 512 + lane * 8;
;           *(float4*)op = make_float4(y[i * 8 + 0], y[i * 8 + 1], y[i * 8 + 2], y[i * 8 + 3]);
;           *(float4*)(op + 4) = make_float4(y[i * 8 + 4], y[i * 8 + 5], y[i * 8 + 6], y[i * 8 + 7]);
;         } else {
;           uint4 o;
;           o.x = pack2(y[i * 8 + 0], y[i * 8 + 1]); o.y = pack2(y[i * 8 + 2], y[i * 8 + 3]);
;           o.z = pack2(y[i * 8 + 4], y[i * 8 + 5]); o.w = pack2(y[i * 8 + 6], y[i * 8 + 7]);
;           *(uint4*)(xb + (size_t)row * DM + i * 512 + lane * 8) = o;
;         }
;       }
.LBB0_1289:
	s_or_b64 exec, exec, s[26:27]
	v_lshlrev_b32_e32 v64, 16, v46
	v_and_b32_e32 v65, 0xffff0000, v46
	v_lshlrev_b32_e32 v46, 16, v47
	v_and_b32_e32 v47, 0xffff0000, v47
	v_lshlrev_b32_e32 v74, 16, v42
	v_and_b32_e32 v75, 0xffff0000, v42
	v_lshlrev_b32_e32 v76, 16, v43
	v_and_b32_e32 v77, 0xffff0000, v43
	v_pk_mul_f32 v[42:43], v[64:65], v[64:65]
	v_lshlrev_b32_e32 v78, 16, v44
	v_and_b32_e32 v79, 0xffff0000, v44
	v_lshlrev_b32_e32 v80, 16, v45
	v_and_b32_e32 v81, 0xffff0000, v45
	v_pk_mul_f32 v[44:45], v[46:47], v[46:47]
	v_add_f32_e32 v0, v42, v43
	v_lshlrev_b32_e32 v72, 16, v48
	v_and_b32_e32 v73, 0xffff0000, v48
	v_add_f32_e32 v0, v0, v44
	v_pk_mul_f32 v[82:83], v[72:73], v[72:73]
	v_add_f32_e32 v0, v45, v0
	v_lshlrev_b32_e32 v48, 16, v49
	v_and_b32_e32 v49, 0xffff0000, v49
	v_add_f32_e32 v0, v82, v0
	v_pk_mul_f32 v[84:85], v[48:49], v[48:49]
	v_add_f32_e32 v0, v83, v0
	v_add_f32_e32 v0, v84, v0
	v_pk_mul_f32 v[86:87], v[74:75], v[74:75]
	v_add_f32_e32 v0, v85, v0
	v_add_f32_e32 v0, v86, v0
	v_pk_mul_f32 v[88:89], v[76:77], v[76:77]
	v_add_f32_e32 v0, v87, v0
	v_add_f32_e32 v0, v88, v0
	v_pk_mul_f32 v[90:91], v[78:79], v[78:79]
	v_add_f32_e32 v0, v89, v0
	v_add_f32_e32 v0, v90, v0
	v_pk_mul_f32 v[92:93], v[80:81], v[80:81]
	v_add_f32_e32 v0, v91, v0
	v_add_f32_e32 v0, v92, v0
	v_add_f32_e32 v0, v93, v0
	ds_bpermute_b32 v42, v66, v0
	v_lshlrev_b32_e32 v82, 16, v34
	v_and_b32_e32 v83, 0xffff0000, v34
	v_lshlrev_b32_e32 v84, 16, v35
	v_and_b32_e32 v85, 0xffff0000, v35
	s_waitcnt lgkmcnt(0)
	v_add_f32_e32 v0, v0, v42
	ds_bpermute_b32 v42, v67, v0
	v_lshlrev_b32_e32 v86, 16, v36
	v_and_b32_e32 v87, 0xffff0000, v36
	v_lshlrev_b32_e32 v88, 16, v37
	v_and_b32_e32 v89, 0xffff0000, v37
	s_waitcnt lgkmcnt(0)
	v_add_f32_e32 v0, v0, v42
	ds_bpermute_b32 v43, v68, v0
	v_lshlrev_b32_e32 v42, 16, v38
	v_lshlrev_b32_e32 v44, 16, v40
	s_waitcnt lgkmcnt(0)
	v_add_f32_e32 v0, v0, v43
	ds_bpermute_b32 v45, v69, v0
	v_and_b32_e32 v43, 0xffff0000, v38
	v_lshlrev_b32_e32 v38, 16, v39
	v_and_b32_e32 v39, 0xffff0000, v39
	s_waitcnt lgkmcnt(0)
	v_add_f32_e32 v0, v0, v45
	ds_bpermute_b32 v51, v70, v0
	v_and_b32_e32 v45, 0xffff0000, v40
	v_lshlrev_b32_e32 v40, 16, v41
	v_and_b32_e32 v41, 0xffff0000, v41
	s_waitcnt lgkmcnt(0)
	v_add_f32_e32 v0, v0, v51
	ds_bpermute_b32 v51, v71, v0
	s_waitcnt lgkmcnt(0)
	v_add_f32_e32 v0, v0, v51
	v_fmamk_f32 v0, v0, 0x3a800000, v216
	v_mul_f32_e32 v34, 0x4b800000, v0
	v_cmp_gt_f32_e32 vcc, s44, v0
	s_nop 1
	v_cndmask_b32_e32 v0, v0, v34, vcc
	v_rsq_f32_e32 v0, v0
	s_nop 0
	v_mul_f32_e32 v34, 0x45800000, v0
	v_cndmask_b32_e32 v0, v0, v34, vcc
	v_pk_mul_f32 v[34:35], v[0:1], v[64:65] op_sel_hi:[0,1]
	v_pk_mul_f32 v[36:37], v[0:1], v[46:47] op_sel_hi:[0,1]
	v_pk_fma_f32 v[34:35], v[6:7], v[34:35], v[42:43]
	v_pk_fma_f32 v[36:37], v[8:9], v[36:37], v[38:39]
	v_pk_mul_f32 v[38:39], v[0:1], v[72:73] op_sel_hi:[0,1]
	v_pk_mul_f32 v[42:43], v[0:1], v[48:49] op_sel_hi:[0,1]
	v_pk_fma_f32 v[38:39], v[2:3], v[38:39], v[44:45]
	v_pk_fma_f32 v[40:41], v[4:5], v[42:43], v[40:41]
	v_pk_mul_f32 v[42:43], v[0:1], v[74:75] op_sel_hi:[0,1]
	v_pk_mul_f32 v[44:45], v[0:1], v[76:77] op_sel_hi:[0,1]
	v_pk_mul_f32 v[46:47], v[0:1], v[78:79] op_sel_hi:[0,1]
	v_pk_mul_f32 v[48:49], v[0:1], v[80:81] op_sel_hi:[0,1]
	v_pk_fma_f32 v[42:43], v[14:15], v[42:43], v[82:83]
	v_pk_fma_f32 v[44:45], v[16:17], v[44:45], v[84:85]
	v_pk_fma_f32 v[46:47], v[10:11], v[46:47], v[86:87]
	s_andn2_b64 vcc, exec, s[22:23]
	v_pk_fma_f32 v[48:49], v[12:13], v[48:49], v[88:89]
	s_cbranch_vccnz .LBB0_1298
	v_lshl_add_u64 v[64:65], v[54:55], 0, v[52:53]
	s_mov_b64 s[26:27], -1
	s_and_b64 vcc, exec, s[10:11]
	s_cbranch_vccz .LBB0_1294
	v_add_co_u32_e32 v76, vcc, 0x61a6000, v64
	v_cvt_pk_bf16_f32 v72, v34, v35
	v_cvt_pk_bf16_f32 v73, v36, v37
	v_cvt_pk_bf16_f32 v74, v38, v39
	v_cvt_pk_bf16_f32 v75, v40, v41
	v_addc_co_u32_e32 v77, vcc, 0, v65, vcc
	global_store_dwordx4 v[76:77], v[72:75], off
	s_cbranch_execz .LBB0_1295

; __device__ __forceinline__ int opaque_tid() { int t = threadIdx.x; asm volatile("" : "+v"(t)); return t; }
; __device__ void attn_item(const Params& p, int layer, int item, int dry) {
;     ...
;   const int tid = opaque_tid(), wid = tid >> 6, lane = tid & 63, r = lane & 15, quad = lane >> 4;
;   bf16_t* cat = (bf16_t*)(ws + O_S + S_CAT);
;   const bf16_t* kv = (const bf16_t*)(ws + O_KV) + layer * 512;
;   const int tile = item >> 2, h = item & 3;
;   const int tok0 = tile * 128;
;   const int seq = tok0 < 32768 ? (tok0 >> 11) : 16 + ((tok0 - 32768) >> 12);
;   bf16_t* Ks = (bf16_t*)smem;
;   bf16_t* Vt = (bf16_t*)(smem + 256 * 72 * 2);
;   const bf16_t* kvs = kv + (size_t)seq * 256 * 1024;
;   for (int i = 0; i < 4; ++i) {
;     int idx = tid + 512 * i;
;     int m = idx >> 3, d0 = (idx & 7) * 8;
;     uint4 uk = *(const uint4*)(kvs + (size_t)m * 1024 + h * 64 + d0);
;     *(uint4*)(Ks + m * 72 + d0) = uk;
;     uint4 uv = *(const uint4*)(kvs + (size_t)m * 1024 + 256 + h * 64 + d0);
;     unsigned uu[4] = {uv.x, uv.y, uv.z, uv.w};
;     for (int j = 0; j < 8; ++j) Vt[(d0 + j) * 264 + m] = (bf16_t)((j & 1) ? (uu[j >> 1] >> 16) : (uu[j >> 1] & 0xffff));
;   }
;   __syncthreads();
;   const int t = tok0 + wid * 16 + r;
;   bf16_t* qp = cat + (size_t)t * 1024 + 768 + h * 64;
;   bf16x8 qf[2];
;   qf[0] = *(const bf16x8*)(qp + quad * 8);
;   qf[1] = *(const bf16x8*)(qp + 32 + quad * 8);
.LBB0_1348:
	s_and_b64 vcc, exec, s[4:5]
	s_cbranch_vccz .LBB0_1365
	s_lshl_b32 s4, s27, 5
	s_and_b32 s6, s4, 0xffffff80
	s_addk_i32 s4, 0x8000
	s_lshr_b32 s4, s4, 12
	s_ashr_i32 s5, s27, 6
	s_add_i32 s4, s4, 16
	s_cmp_lt_i32 s6, 0x8000
	s_waitcnt vmcnt(2)
	v_mov_b32_e32 v44, v208
	s_cselect_b32 s4, s5, s4
	s_ashr_i32 s5, s4, 31
	v_add_u32_e32 v10, 0x200, v44
	v_add_u32_e32 v18, 0x400, v44
	v_add_u32_e32 v26, 0x600, v44
	s_lshl_b64 s[4:5], s[4:5], 19
	s_waitcnt vmcnt(0)
	v_ashrrev_i32_e32 v34, 3, v44
	v_ashrrev_i32_e32 v36, 3, v10
	v_ashrrev_i32_e32 v38, 3, v18
	v_ashrrev_i32_e32 v40, 3, v26
	s_add_u32 s4, s77, s4
	v_ashrrev_i32_e32 v35, 31, v34
	v_ashrrev_i32_e32 v37, 31, v36
	v_ashrrev_i32_e32 v39, 31, v38
	v_ashrrev_i32_e32 v41, 31, v40
	s_addc_u32 s5, s78, s5
	v_lshlrev_b32_e32 v0, 3, v44
	v_lshlrev_b64 v[2:3], 11, v[34:35]
	s_lshl_b32 s7, s27, 7
	v_lshlrev_b64 v[10:11], 11, v[36:37]
	v_lshlrev_b64 v[18:19], 11, v[38:39]
	v_lshlrev_b64 v[26:27], 11, v[40:41]
	v_and_b32_e32 v42, 56, v0
	v_lshl_add_u64 v[2:3], s[4:5], 0, v[2:3]
	s_and_b32 s66, s7, 0x180
	v_lshl_add_u64 v[10:11], s[4:5], 0, v[10:11]
	v_lshl_add_u64 v[18:19], s[4:5], 0, v[18:19]
	v_lshl_add_u64 v[26:27], s[4:5], 0, v[26:27]
	v_lshlrev_b32_e32 v0, 1, v42
	v_lshl_add_u64 v[2:3], v[2:3], 0, s[66:67]
	v_lshl_add_u64 v[10:11], v[10:11], 0, s[66:67]
	v_lshl_add_u64 v[18:19], v[18:19], 0, s[66:67]
	v_lshl_add_u64 v[26:27], v[26:27], 0, s[66:67]
	v_lshl_add_u64 v[6:7], v[2:3], 0, v[0:1]
	v_lshl_add_u64 v[14:15], v[10:11], 0, v[0:1]
	v_lshl_add_u64 v[22:23], v[18:19], 0, v[0:1]
	v_lshl_add_u64 v[30:31], v[26:27], 0, v[0:1]
	global_load_dwordx4 v[2:5], v[6:7], off
	s_nop 0
	global_load_dwordx4 v[6:9], v[6:7], off offset:512
	s_nop 0
	global_load_dwordx4 v[10:13], v[14:15], off
	s_nop 0
	global_load_dwordx4 v[14:17], v[14:15], off offset:512
	s_nop 0
	global_load_dwordx4 v[18:21], v[22:23], off
	s_nop 0
	global_load_dwordx4 v[22:25], v[22:23], off offset:512
	s_nop 0
	global_load_dwordx4 v[26:29], v[30:31], off
	s_nop 0
	global_load_dwordx4 v[30:33], v[30:31], off offset:512
	s_movk_i32 s7, 0x90
	v_mul_u32_u24_e32 v41, 0x251, v42
	v_mad_u64_u32 v[42:43], s[4:5], v34, s7, v[0:1]
	v_lshl_add_u32 v43, v34, 1, v41
	v_mad_u64_u32 v[34:35], s[4:5], v36, s7, v[0:1]
	v_lshl_add_u32 v35, v36, 1, v41
	v_mad_u64_u32 v[36:37], s[4:5], v38, s7, v[0:1]
	v_lshl_add_u32 v37, v38, 1, v41
	v_mad_u64_u32 v[38:39], s[4:5], v40, s7, v[0:1]
	v_lshl_add_u32 v0, v40, 1, v41
	v_and_b32_e32 v60, 15, v44
	v_bfe_u32 v61, v44, 4, 2
	s_mov_b64 s[4:5], 0xe1a6600
	s_waitcnt vmcnt(7)
	ds_write_b128 v42, v[2:5]
	s_waitcnt vmcnt(6)
	ds_write_b16 v43, v6 offset:36864
	ds_write_b16_d16_hi v43, v6 offset:37456
	ds_write_b16 v43, v7 offset:38048
	ds_write_b16_d16_hi v43, v7 offset:38640
	ds_write_b16 v43, v8 offset:39232
	ds_write_b16_d16_hi v43, v8 offset:39824
	ds_write_b16 v43, v9 offset:40416
	ds_write_b16_d16_hi v43, v9 offset:41008
	s_waitcnt vmcnt(5)
	ds_write_b128 v34, v[10:13]
	s_waitcnt vmcnt(4)
	ds_write_b16 v35, v14 offset:36864
	ds_write_b16_d16_hi v35, v14 offset:37456
	ds_write_b16 v35, v15 offset:38048
	ds_write_b16_d16_hi v35, v15 offset:38640
	ds_write_b16 v35, v16 offset:39232
	ds_write_b16_d16_hi v35, v16 offset:39824
	ds_write_b16 v35, v17 offset:40416
	ds_write_b16_d16_hi v35, v17 offset:41008
	s_waitcnt vmcnt(3)
	ds_write_b128 v36, v[18:21]
	s_waitcnt vmcnt(2)
	ds_write_b16 v37, v22 offset:36864
	ds_write_b16_d16_hi v37, v22 offset:37456
	ds_write_b16 v37, v23 offset:38048
	ds_write_b16_d16_hi v37, v23 offset:38640
	ds_write_b16 v37, v24 offset:39232
	ds_write_b16_d16_hi v37, v24 offset:39824
	ds_write_b16 v37, v25 offset:40416
	ds_write_b16_d16_hi v37, v25 offset:41008
	s_waitcnt vmcnt(1)
	ds_write_b128 v38, v[26:29]
	s_waitcnt vmcnt(0)
	ds_write_b16 v0, v30 offset:36864
	ds_write_b16_d16_hi v0, v30 offset:37456
	ds_write_b16 v0, v31 offset:38048
	ds_write_b16_d16_hi v0, v31 offset:38640
	ds_write_b16 v0, v32 offset:39232
	ds_write_b16_d16_hi v0, v32 offset:39824
	ds_write_b16 v0, v33 offset:40416
	ds_write_b16_d16_hi v0, v33 offset:41008
	v_ashrrev_i32_e32 v0, 2, v44
	v_and_b32_e32 v0, -16, v0
	v_add_u32_e32 v0, s6, v0
	v_or_b32_e32 v2, v0, v60
	v_ashrrev_i32_e32 v3, 31, v2
	v_lshlrev_b64 v[2:3], 11, v[2:3]
	v_lshl_add_u64 v[2:3], s[14:15], 0, v[2:3]
	v_lshl_add_u64 v[2:3], v[2:3], 0, s[66:67]
	v_lshl_add_u64 v[54:55], v[2:3], 0, s[4:5]
	v_lshlrev_b32_e32 v0, 4, v61
	v_lshl_add_u64 v[34:35], v[54:55], 0, v[0:1]
	global_load_dwordx4 v[2:5], v[34:35], off
	global_load_dwordx4 v[56:59], v[34:35], off offset:64
	s_waitcnt lgkmcnt(0)
	s_barrier
; __device__ void attn_item(const Params& p, int layer, int item, int dry) {
;     ...
;   const int t = tok0 + wid * 16 + r;
;   bf16_t* qp = cat + (size_t)t * 1024 + 768 + h * 64;
;   bf16x8 qf[2];
;   qf[0] = *(const bf16x8*)(qp + quad * 8);
;   qf[1] = *(const bf16x8*)(qp + 32 + quad * 8);
;   f32x4 s[16];
;   for (int mt = 0; mt < 16; ++mt) {
;     s[mt] = f32x4{0.f, 0.f, 0.f, 0.f};
;     for (int ks = 0; ks < 2; ++ks) {
;       bf16x8 a = *(const bf16x8*)(Ks + (mt * 16 + r) * 72 + ks * 32 + quad * 8);
;       s[mt] = __builtin_amdgcn_mfma_f32_16x16x32_bf16(a, qf[ks], s[mt], 0, 0, 0);
;     }
;   }
;   float mx = -1e30f;
;   for (int mt = 0; mt < 16; ++mt)
;     for (int j = 0; j < 4; ++j) mx = fmaxf(mx, s[mt][j]);
;   mx = fmaxf(mx, __shfl_xor(mx, 16));
;   mx = fmaxf(mx, __shfl_xor(mx, 32));
	v_mad_u32_u24 v98, v60, s7, v0
	ds_read_b128 v[38:41], v98 offset:18432
	ds_read_b128 v[6:9], v98
	ds_read_b128 v[10:13], v98 offset:2304
	ds_read_b128 v[14:17], v98 offset:4608
	ds_read_b128 v[18:21], v98 offset:6912
	ds_read_b128 v[22:25], v98 offset:9216
	ds_read_b128 v[26:29], v98 offset:11520
	ds_read_b128 v[30:33], v98 offset:13824
	ds_read_b128 v[34:37], v98 offset:16128
	s_mov_b32 s4, 0xf149f2ca
	s_waitcnt vmcnt(1) lgkmcnt(8)
	v_mfma_f32_16x16x32_bf16 v[62:65], v[38:41], v[2:5], 0
	ds_read_b128 v[38:41], v98 offset:20736
	s_waitcnt lgkmcnt(0)
	v_mfma_f32_16x16x32_bf16 v[66:69], v[38:41], v[2:5], 0
	ds_read_b128 v[38:41], v98 offset:23040
	s_waitcnt lgkmcnt(0)
	v_mfma_f32_16x16x32_bf16 v[70:73], v[38:41], v[2:5], 0
	ds_read_b128 v[38:41], v98 offset:25344
	s_waitcnt lgkmcnt(0)
	v_mfma_f32_16x16x32_bf16 v[74:77], v[38:41], v[2:5], 0
	ds_read_b128 v[38:41], v98 offset:27648
	s_waitcnt lgkmcnt(0)
	v_mfma_f32_16x16x32_bf16 v[78:81], v[38:41], v[2:5], 0
	ds_read_b128 v[38:41], v98 offset:29952
	s_waitcnt lgkmcnt(0)
	v_mfma_f32_16x16x32_bf16 v[82:85], v[38:41], v[2:5], 0
	ds_read_b128 v[38:41], v98 offset:64
	v_mfma_f32_16x16x32_bf16 v[6:9], v[6:9], v[2:5], 0
	s_waitcnt vmcnt(0) lgkmcnt(0)
	v_mfma_f32_16x16x32_bf16 v[86:89], v[38:41], v[56:59], v[6:9]
	s_nop 5
	ds_read_b128 v[6:9], v98 offset:2368
	v_mfma_f32_16x16x32_bf16 v[10:13], v[10:13], v[2:5], 0
	s_waitcnt lgkmcnt(0)
	v_mfma_f32_16x16x32_bf16 v[90:93], v[6:9], v[56:59], v[10:13]
	ds_read_b128 v[6:9], v98 offset:4672
	v_mfma_f32_16x16x32_bf16 v[14:17], v[14:17], v[2:5], 0
	s_waitcnt lgkmcnt(0)
	v_mfma_f32_16x16x32_bf16 v[94:97], v[6:9], v[56:59], v[14:17]
	ds_read_b128 v[6:9], v98 offset:6976
	v_mfma_f32_16x16x32_bf16 v[18:21], v[18:21], v[2:5], 0
	s_waitcnt lgkmcnt(0)
	v_mfma_f32_16x16x32_bf16 v[50:53], v[6:9], v[56:59], v[18:21]
	ds_read_b128 v[6:9], v98 offset:9280
	v_mfma_f32_16x16x32_bf16 v[22:25], v[22:25], v[2:5], 0
	s_waitcnt lgkmcnt(0)
	v_mfma_f32_16x16x32_bf16 v[46:49], v[6:9], v[56:59], v[22:25]
	ds_read_b128 v[6:9], v98 offset:11584
	v_mfma_f32_16x16x32_bf16 v[26:29], v[26:29], v[2:5], 0
	s_waitcnt lgkmcnt(0)
	v_mfma_f32_16x16x32_bf16 v[42:45], v[6:9], v[56:59], v[26:29]
	ds_read_b128 v[6:9], v98 offset:13888
	v_mfma_f32_16x16x32_bf16 v[30:33], v[30:33], v[2:5], 0
	s_waitcnt lgkmcnt(0)
	v_mfma_f32_16x16x32_bf16 v[38:41], v[6:9], v[56:59], v[30:33]
	ds_read_b128 v[6:9], v98 offset:16192
	v_mfma_f32_16x16x32_bf16 v[34:37], v[34:37], v[2:5], 0
	s_waitcnt lgkmcnt(0)
	v_mfma_f32_16x16x32_bf16 v[34:37], v[6:9], v[56:59], v[34:37]
	ds_read_b128 v[6:9], v98 offset:18496
	s_waitcnt lgkmcnt(0)
	v_mfma_f32_16x16x32_bf16 v[30:33], v[6:9], v[56:59], v[62:65]
	ds_read_b128 v[6:9], v98 offset:20800
	s_nop 1
	ds_read_b128 v[62:65], v98 offset:32320
	s_waitcnt lgkmcnt(1)
	v_mfma_f32_16x16x32_bf16 v[26:29], v[6:9], v[56:59], v[66:69]
	ds_read_b128 v[6:9], v98 offset:23104
	s_waitcnt lgkmcnt(0)
	v_mfma_f32_16x16x32_bf16 v[22:25], v[6:9], v[56:59], v[70:73]
	ds_read_b128 v[6:9], v98 offset:25408
	s_waitcnt lgkmcnt(0)
	v_mfma_f32_16x16x32_bf16 v[18:21], v[6:9], v[56:59], v[74:77]
	ds_read_b128 v[6:9], v98 offset:27712
	s_waitcnt lgkmcnt(0)
	v_mfma_f32_16x16x32_bf16 v[14:17], v[6:9], v[56:59], v[78:81]
	ds_read_b128 v[6:9], v98 offset:30016
	s_waitcnt lgkmcnt(0)
	v_mfma_f32_16x16x32_bf16 v[10:13], v[6:9], v[56:59], v[82:85]
	ds_read_b128 v[6:9], v98 offset:32256
	s_waitcnt lgkmcnt(0)
	v_mfma_f32_16x16x32_bf16 v[6:9], v[6:9], v[2:5], 0
	v_mfma_f32_16x16x32_bf16 v[6:9], v[62:65], v[56:59], v[6:9]
	ds_read_b128 v[62:65], v98 offset:34560
	s_waitcnt lgkmcnt(0)
	v_mfma_f32_16x16x32_bf16 v[2:5], v[62:65], v[2:5], 0
	ds_read_b128 v[62:65], v98 offset:34624
	s_waitcnt lgkmcnt(0)
	v_mfma_f32_16x16x32_bf16 v[2:5], v[62:65], v[56:59], v[2:5]
	v_max3_f32 v56, v86, s4, v87
	v_max3_f32 v56, v56, v88, v89
	v_max3_f32 v56, v56, v90, v91
	v_max3_f32 v56, v56, v92, v93
	v_max3_f32 v56, v56, v94, v95
	v_max3_f32 v56, v56, v96, v97
	v_max3_f32 v56, v56, v50, v51
	v_max3_f32 v56, v56, v52, v53
	v_max3_f32 v56, v56, v46, v47
	v_max3_f32 v56, v56, v48, v49
	v_max3_f32 v56, v56, v42, v43
	v_max3_f32 v56, v56, v44, v45
	v_max3_f32 v56, v56, v38, v39
	v_max3_f32 v56, v56, v40, v41
	v_max3_f32 v56, v56, v34, v35
	v_max3_f32 v56, v56, v36, v37
	v_max3_f32 v56, v56, v30, v31
	v_max3_f32 v56, v56, v32, v33
	v_max3_f32 v56, v56, v26, v27
	v_max3_f32 v56, v56, v28, v29
	v_max3_f32 v56, v56, v22, v23
	v_max3_f32 v56, v56, v24, v25
	v_max3_f32 v56, v56, v18, v19
	v_max3_f32 v56, v56, v20, v21
	v_max3_f32 v56, v56, v14, v15
	v_max3_f32 v56, v56, v16, v17
	v_max3_f32 v56, v56, v10, v11
	v_max3_f32 v56, v56, v12, v13
	v_and_b32_e32 v58, 64, v228
	v_max3_f32 v56, v56, v6, v7
	v_xor_b32_e32 v57, 16, v228
	v_add_u32_e32 v59, 64, v58
	v_max3_f32 v56, v56, v8, v9
	v_cmp_lt_i32_e32 vcc, v57, v59
	v_max3_f32 v56, v56, v2, v3
	v_max3_f32 v56, v56, v4, v5
	v_cndmask_b32_e32 v57, v228, v57, vcc
	v_lshlrev_b32_e32 v58, 2, v57
	ds_bpermute_b32 v57, v58, v56
	s_movk_i32 s4, 0x210
	s_waitcnt lgkmcnt(0)
	v_max_f32_e32 v57, v57, v57
	v_max_f32_e32 v62, v56, v57
	v_xor_b32_e32 v56, 32, v228
	v_cmp_lt_i32_e32 vcc, v56, v59
	s_nop 1
	v_cndmask_b32_e32 v56, v228, v56, vcc
	v_lshlrev_b32_e32 v57, 2, v56
	ds_bpermute_b32 v59, v57, v62
	v_lshlrev_b32_e32 v56, 3, v61
	v_sub_u32_e32 v0, v0, v56
	s_andn2_b64 vcc, exec, s[24:25]
	s_waitcnt lgkmcnt(0)
; __device__ void attn_item(const Params& p, int layer, int item, int dry) {
;     ...
;   float sum = 0.f;
;   for (int mt = 0; mt < 16; ++mt)
;     for (int j = 0; j < 4; ++j) {
;       float e = __expf((s[mt][j] - mx) * 0.125f);
;       s[mt][j] = e;
;       sum += e;
;     }
;   sum += __shfl_xor(sum, 16);
;   sum += __shfl_xor(sum, 32);
	v_max_f32_e32 v59, v59, v59
	v_max_f32_e32 v59, v62, v59
	v_sub_f32_e32 v61, v86, v59
	v_mul_f32_e32 v61, 0x3e000000, v61
	v_mul_f32_e32 v61, 0x3fb8aa3b, v61
	v_exp_f32_e32 v65, v61
	v_sub_f32_e32 v61, v87, v59
	v_mul_f32_e32 v61, 0x3e000000, v61
	v_sub_f32_e32 v62, v90, v59
	v_mul_f32_e32 v61, 0x3fb8aa3b, v61
	v_mul_f32_e32 v62, 0x3e000000, v62
	v_exp_f32_e32 v66, v61
	v_sub_f32_e32 v61, v88, v59
	v_mul_f32_e32 v62, 0x3fb8aa3b, v62
	v_mul_f32_e32 v61, 0x3e000000, v61
	v_exp_f32_e32 v68, v62
	v_sub_f32_e32 v62, v91, v59
	v_mul_f32_e32 v61, 0x3fb8aa3b, v61
	v_mul_f32_e32 v62, 0x3e000000, v62
	v_exp_f32_e32 v67, v61
	v_sub_f32_e32 v61, v89, v59
	v_mul_f32_e32 v62, 0x3fb8aa3b, v62
	v_mul_f32_e32 v61, 0x3e000000, v61
	v_exp_f32_e32 v75, v62
	v_sub_f32_e32 v62, v92, v59
	v_mul_f32_e32 v61, 0x3fb8aa3b, v61
	v_mul_f32_e32 v62, 0x3e000000, v62
	v_exp_f32_e32 v74, v61
	v_mul_f32_e32 v62, 0x3fb8aa3b, v62
	v_add_f32_e32 v61, 0, v65
	v_exp_f32_e32 v69, v62
	v_sub_f32_e32 v62, v93, v59
	v_add_f32_e32 v61, v66, v61
	v_mul_f32_e32 v62, 0x3e000000, v62
	v_add_f32_e32 v61, v67, v61
	v_mul_f32_e32 v62, 0x3fb8aa3b, v62
	v_add_f32_e32 v61, v74, v61
	v_exp_f32_e32 v70, v62
	v_add_f32_e32 v61, v68, v61
	v_add_f32_e32 v61, v75, v61
	v_sub_f32_e32 v50, v50, v59
	v_add_f32_e32 v61, v69, v61
	v_mul_f32_e32 v50, 0x3e000000, v50
	v_add_f32_e32 v71, v70, v61
	v_sub_f32_e32 v61, v94, v59
	v_mul_f32_e32 v50, 0x3fb8aa3b, v50
	v_mul_f32_e32 v61, 0x3e000000, v61
	v_sub_f32_e32 v62, v95, v59
	v_exp_f32_e32 v90, v50
	v_sub_f32_e32 v50, v51, v59
	v_mul_f32_e32 v61, 0x3fb8aa3b, v61
	v_mul_f32_e32 v62, 0x3e000000, v62
	v_sub_f32_e32 v63, v96, v59
	v_mul_f32_e32 v50, 0x3e000000, v50
	v_exp_f32_e32 v61, v61
	v_mul_f32_e32 v62, 0x3fb8aa3b, v62
	v_mul_f32_e32 v63, 0x3e000000, v63
	v_sub_f32_e32 v64, v97, v59
	v_mul_f32_e32 v50, 0x3fb8aa3b, v50
	v_exp_f32_e32 v62, v62
	v_mul_f32_e32 v63, 0x3fb8aa3b, v63
	v_mul_f32_e32 v64, 0x3e000000, v64
	v_exp_f32_e32 v91, v50
	v_sub_f32_e32 v50, v52, v59
	v_exp_f32_e32 v63, v63
	v_mul_f32_e32 v64, 0x3fb8aa3b, v64
	v_mul_f32_e32 v50, 0x3e000000, v50
	v_exp_f32_e32 v64, v64
	v_mul_f32_e32 v50, 0x3fb8aa3b, v50
	v_add_f32_e32 v71, v61, v71
	v_exp_f32_e32 v92, v50
	v_sub_f32_e32 v50, v53, v59
	v_add_f32_e32 v71, v62, v71
	v_mul_f32_e32 v50, 0x3e000000, v50
	v_sub_f32_e32 v46, v46, v59
	v_add_f32_e32 v71, v63, v71
	v_mul_f32_e32 v50, 0x3fb8aa3b, v50
	v_mul_f32_e32 v46, 0x3e000000, v46
	v_sub_f32_e32 v47, v47, v59
	v_add_f32_e32 v71, v64, v71
	v_exp_f32_e32 v53, v50
	v_mul_f32_e32 v46, 0x3fb8aa3b, v46
	v_mul_f32_e32 v47, 0x3e000000, v47
	v_sub_f32_e32 v48, v48, v59
	v_add_f32_e32 v50, v90, v71
	v_exp_f32_e32 v46, v46
	v_mul_f32_e32 v47, 0x3fb8aa3b, v47
	v_mul_f32_e32 v48, 0x3e000000, v48
	v_sub_f32_e32 v49, v49, v59
	v_add_f32_e32 v50, v91, v50
	v_exp_f32_e32 v47, v47
	v_mul_f32_e32 v48, 0x3fb8aa3b, v48
	v_mul_f32_e32 v49, 0x3e000000, v49
	v_add_f32_e32 v50, v92, v50
	v_exp_f32_e32 v48, v48
	v_mul_f32_e32 v49, 0x3fb8aa3b, v49
	v_add_f32_e32 v50, v53, v50
	v_exp_f32_e32 v49, v49
	v_add_f32_e32 v50, v46, v50
	v_sub_f32_e32 v42, v42, v59
	v_add_f32_e32 v50, v47, v50
	v_mul_f32_e32 v42, 0x3e000000, v42
	v_add_f32_e32 v50, v48, v50
	v_mul_f32_e32 v42, 0x3fb8aa3b, v42
	v_add_f32_e32 v71, v49, v50
	v_exp_f32_e32 v50, v42
	v_sub_f32_e32 v42, v43, v59
	v_mul_f32_e32 v42, 0x3e000000, v42
	v_mul_f32_e32 v42, 0x3fb8aa3b, v42
	v_exp_f32_e32 v51, v42
	v_sub_f32_e32 v42, v44, v59
	v_mul_f32_e32 v42, 0x3e000000, v42
	v_mul_f32_e32 v42, 0x3fb8aa3b, v42
	v_exp_f32_e32 v52, v42
	v_sub_f32_e32 v42, v45, v59
	v_mul_f32_e32 v42, 0x3e000000, v42
	v_sub_f32_e32 v38, v38, v59
	v_mul_f32_e32 v42, 0x3fb8aa3b, v42
	v_mul_f32_e32 v38, 0x3e000000, v38
	v_sub_f32_e32 v39, v39, v59
	v_exp_f32_e32 v45, v42
	v_mul_f32_e32 v38, 0x3fb8aa3b, v38
	v_mul_f32_e32 v39, 0x3e000000, v39
	v_sub_f32_e32 v40, v40, v59
	v_add_f32_e32 v42, v50, v71
	v_exp_f32_e32 v38, v38
	v_mul_f32_e32 v39, 0x3fb8aa3b, v39
	v_mul_f32_e32 v40, 0x3e000000, v40
	v_sub_f32_e32 v41, v41, v59
	v_add_f32_e32 v42, v51, v42
	v_exp_f32_e32 v39, v39
	v_mul_f32_e32 v40, 0x3fb8aa3b, v40
	v_mul_f32_e32 v41, 0x3e000000, v41
	v_add_f32_e32 v42, v52, v42
	v_exp_f32_e32 v40, v40
	v_mul_f32_e32 v41, 0x3fb8aa3b, v41
	v_add_f32_e32 v42, v45, v42
	v_exp_f32_e32 v41, v41
	v_add_f32_e32 v42, v38, v42
	v_sub_f32_e32 v34, v34, v59
	v_add_f32_e32 v42, v39, v42
	v_mul_f32_e32 v34, 0x3e000000, v34
	v_add_f32_e32 v42, v40, v42
	v_mul_f32_e32 v34, 0x3fb8aa3b, v34
	v_add_f32_e32 v71, v41, v42
	v_exp_f32_e32 v42, v34
	v_sub_f32_e32 v34, v35, v59
	v_mul_f32_e32 v34, 0x3e000000, v34
	v_mul_f32_e32 v34, 0x3fb8aa3b, v34
	v_exp_f32_e32 v43, v34
	v_sub_f32_e32 v34, v36, v59
	v_mul_f32_e32 v34, 0x3e000000, v34
	v_mul_f32_e32 v34, 0x3fb8aa3b, v34
	v_exp_f32_e32 v44, v34
	v_sub_f32_e32 v34, v37, v59
	v_mul_f32_e32 v34, 0x3e000000, v34
	v_sub_f32_e32 v30, v30, v59
	v_mul_f32_e32 v34, 0x3fb8aa3b, v34
	v_mul_f32_e32 v30, 0x3e000000, v30
	v_sub_f32_e32 v31, v31, v59
	v_exp_f32_e32 v37, v34
	v_mul_f32_e32 v30, 0x3fb8aa3b, v30
	v_mul_f32_e32 v31, 0x3e000000, v31
	v_sub_f32_e32 v32, v32, v59
	v_add_f32_e32 v34, v42, v71
	v_exp_f32_e32 v30, v30
	v_mul_f32_e32 v31, 0x3fb8aa3b, v31
	v_mul_f32_e32 v32, 0x3e000000, v32
	v_sub_f32_e32 v33, v33, v59
	v_add_f32_e32 v34, v43, v34
	v_exp_f32_e32 v31, v31
	v_mul_f32_e32 v32, 0x3fb8aa3b, v32
	v_mul_f32_e32 v33, 0x3e000000, v33
	v_add_f32_e32 v34, v44, v34
	v_exp_f32_e32 v32, v32
	v_mul_f32_e32 v33, 0x3fb8aa3b, v33
	v_add_f32_e32 v34, v37, v34
	v_exp_f32_e32 v33, v33
	v_add_f32_e32 v34, v30, v34
	v_sub_f32_e32 v26, v26, v59
	v_add_f32_e32 v34, v31, v34
	v_mul_f32_e32 v26, 0x3e000000, v26
	v_add_f32_e32 v34, v32, v34
; __device__ __forceinline__ unsigned short f2bf(float f) { return (unsigned short)(pack2(f, 0.f) & 0xffffu); }
; __device__ void attn_item(const Params& p, int layer, int item, int dry) {
;     ...
;   for (int mt = 0; mt < 16; ++mt)
;     for (int j = 0; j < 4; ++j) {
;       float e = __expf((s[mt][j] - mx) * 0.125f);
;       s[mt][j] = e;
;       sum += e;
;     }
;   sum += __shfl_xor(sum, 16);
;   sum += __shfl_xor(sum, 32);
;   const float inv = 1.f / sum;
;   f32x4 o[4] = {};
;   for (int ks = 0; ks < 8; ++ks) {
;     bf16x8 pb;
;     for (int j = 0; j < 4; ++j) {
;       pb[j] = (short)f2bf(s[2 * ks][j]);
;       pb[4 + j] = (short)f2bf(s[2 * ks + 1][j]);
;     }
;     for (int dt = 0; dt < 4; ++dt) {
;       const bf16_t* vp = Vt + (dt * 16 + r) * 264 + ks * 32 + quad * 4;
;       uint2 v0 = *(const uint2*)vp, v1 = *(const uint2*)(vp + 16);
;       bf16x8 av;
;       av[0] = (short)(v0.x & 0xffff); av[1] = (short)(v0.x >> 16); av[2] = (short)(v0.y & 0xffff); av[3] = (short)(v0.y >> 16);
;       av[4] = (short)(v1.x & 0xffff); av[5] = (short)(v1.x >> 16); av[6] = (short)(v1.y & 0xffff); av[7] = (short)(v1.y >> 16);
;       o[dt] = __builtin_amdgcn_mfma_f32_16x16x32_bf16(av, pb, o[dt], 0, 0, 0);
	v_mul_f32_e32 v26, 0x3fb8aa3b, v26
	v_add_f32_e32 v71, v33, v34
	v_exp_f32_e32 v34, v26
	v_sub_f32_e32 v26, v27, v59
	v_mul_f32_e32 v26, 0x3e000000, v26
	v_mul_f32_e32 v26, 0x3fb8aa3b, v26
	v_exp_f32_e32 v35, v26
	v_sub_f32_e32 v26, v28, v59
	v_mul_f32_e32 v26, 0x3e000000, v26
	v_mul_f32_e32 v26, 0x3fb8aa3b, v26
	v_exp_f32_e32 v28, v26
	v_sub_f32_e32 v26, v29, v59
	v_mul_f32_e32 v26, 0x3e000000, v26
	v_sub_f32_e32 v22, v22, v59
	v_mul_f32_e32 v26, 0x3fb8aa3b, v26
	v_mul_f32_e32 v22, 0x3e000000, v22
	v_sub_f32_e32 v23, v23, v59
	v_exp_f32_e32 v36, v26
	v_mul_f32_e32 v22, 0x3fb8aa3b, v22
	v_mul_f32_e32 v23, 0x3e000000, v23
	v_sub_f32_e32 v24, v24, v59
	v_add_f32_e32 v26, v34, v71
	v_exp_f32_e32 v22, v22
	v_mul_f32_e32 v23, 0x3fb8aa3b, v23
	v_mul_f32_e32 v24, 0x3e000000, v24
	v_sub_f32_e32 v25, v25, v59
	v_add_f32_e32 v26, v35, v26
	v_exp_f32_e32 v23, v23
	v_mul_f32_e32 v24, 0x3fb8aa3b, v24
	v_mul_f32_e32 v25, 0x3e000000, v25
	v_add_f32_e32 v26, v28, v26
	v_exp_f32_e32 v24, v24
	v_mul_f32_e32 v25, 0x3fb8aa3b, v25
	v_add_f32_e32 v26, v36, v26
	v_exp_f32_e32 v25, v25
	v_add_f32_e32 v26, v22, v26
	v_sub_f32_e32 v18, v18, v59
	v_sub_f32_e32 v20, v20, v59
	v_add_f32_e32 v26, v23, v26
	v_mul_f32_e32 v18, 0x3e000000, v18
	v_sub_f32_e32 v19, v19, v59
	v_mul_f32_e32 v20, 0x3e000000, v20
	v_add_f32_e32 v26, v24, v26
	v_mul_f32_e32 v18, 0x3fb8aa3b, v18
	v_mul_f32_e32 v19, 0x3e000000, v19
	v_mul_f32_e32 v20, 0x3fb8aa3b, v20
	v_add_f32_e32 v29, v25, v26
	v_exp_f32_e32 v18, v18
	v_mul_f32_e32 v19, 0x3fb8aa3b, v19
	v_exp_f32_e32 v26, v20
	v_sub_f32_e32 v20, v21, v59
	v_exp_f32_e32 v19, v19
	v_mul_f32_e32 v20, 0x3e000000, v20
	v_sub_f32_e32 v14, v14, v59
	v_mul_f32_e32 v20, 0x3fb8aa3b, v20
	v_mul_f32_e32 v14, 0x3e000000, v14
	v_sub_f32_e32 v15, v15, v59
	v_exp_f32_e32 v27, v20
	v_mul_f32_e32 v14, 0x3fb8aa3b, v14
	v_mul_f32_e32 v15, 0x3e000000, v15
	v_sub_f32_e32 v16, v16, v59
	v_add_f32_e32 v20, v18, v29
	v_exp_f32_e32 v14, v14
	v_mul_f32_e32 v15, 0x3fb8aa3b, v15
	v_mul_f32_e32 v16, 0x3e000000, v16
	v_sub_f32_e32 v17, v17, v59
	v_add_f32_e32 v20, v19, v20
	v_exp_f32_e32 v15, v15
	v_mul_f32_e32 v16, 0x3fb8aa3b, v16
	v_mul_f32_e32 v17, 0x3e000000, v17
	v_sub_f32_e32 v10, v10, v59
	v_add_f32_e32 v20, v26, v20
	v_exp_f32_e32 v16, v16
	v_mul_f32_e32 v17, 0x3fb8aa3b, v17
	v_mul_f32_e32 v10, 0x3e000000, v10
	v_sub_f32_e32 v11, v11, v59
	v_add_f32_e32 v20, v27, v20
	v_exp_f32_e32 v17, v17
	v_mul_f32_e32 v10, 0x3fb8aa3b, v10
	v_mul_f32_e32 v11, 0x3e000000, v11
	v_sub_f32_e32 v12, v12, v59
	v_add_f32_e32 v20, v14, v20
	v_exp_f32_e32 v10, v10
	v_mul_f32_e32 v11, 0x3fb8aa3b, v11
	v_mul_f32_e32 v12, 0x3e000000, v12
	v_sub_f32_e32 v13, v13, v59
	v_add_f32_e32 v20, v15, v20
	v_exp_f32_e32 v11, v11
	v_mul_f32_e32 v12, 0x3fb8aa3b, v12
	v_mul_f32_e32 v13, 0x3e000000, v13
	v_add_f32_e32 v20, v16, v20
	v_exp_f32_e32 v12, v12
	v_mul_f32_e32 v13, 0x3fb8aa3b, v13
	v_add_f32_e32 v20, v17, v20
	v_exp_f32_e32 v13, v13
	v_add_f32_e32 v20, v10, v20
	v_add_f32_e32 v20, v11, v20
	v_add_f32_e32 v20, v12, v20
	v_add_f32_e32 v86, v13, v20
	v_sub_f32_e32 v7, v7, v59
	v_mul_u32_u24_e32 v176, 0x250, v60
	v_lshrrev_b32_e32 v177, 3, v60
	v_add_u32_e32 v20, v176, v0
	v_lshl_add_u32 v20, v177, 3, v20
	v_mul_f32_e32 v29, 0x3e000000, v7
	v_add_u32_e32 v21, 0x9000, v20
	v_add_u32_e32 v7, 0xb410, v20
	v_add_u32_e32 v0, 0xd820, v20
	v_add_u32_e32 v20, 0xfc30, v20
	v_cvt_pk_bf16_f32 v69, v69, v70
	ds_read2_b64 v[70:73], v21 offset1:4
	v_cvt_pk_bf16_f32 v68, v68, v75
	v_cvt_pk_bf16_f32 v67, v67, v74
	ds_read2_b64 v[74:77], v7 offset0:32 offset1:36
	ds_read2_b64 v[78:81], v0 offset0:64 offset1:68
	ds_read2_b64 v[82:85], v20 offset0:96 offset1:100
	v_sub_f32_e32 v6, v6, v59
	v_mul_f32_e32 v6, 0x3e000000, v6
	v_mul_f32_e32 v6, 0x3fb8aa3b, v6
	v_exp_f32_e32 v6, v6
	s_waitcnt lgkmcnt(3)
	v_bfi_b32 v72, s65, v72, v72
	s_waitcnt lgkmcnt(2)
	v_bfi_b32 v76, s65, v76, v76
	s_waitcnt lgkmcnt(1)
	v_bfi_b32 v80, s65, v80, v80
	v_mul_f32_e32 v29, 0x3fb8aa3b, v29
	s_waitcnt lgkmcnt(0)
	v_bfi_b32 v84, s65, v84, v84
	v_exp_f32_e32 v29, v29
	v_cvt_pk_bf16_f32 v66, v65, v66
	v_add_f32_e32 v60, v6, v86
	ds_read2_b64 v[86:89], v21 offset0:8 offset1:12
	v_mfma_f32_16x16x32_bf16 v[70:73], v[70:73], v[66:69], 0
	v_add_f32_e32 v94, v29, v60
	v_sub_f32_e32 v8, v8, v59
	v_mul_f32_e32 v8, 0x3e000000, v8
	v_mfma_f32_16x16x32_bf16 v[74:77], v[74:77], v[66:69], 0
	s_waitcnt lgkmcnt(0)
	v_bfi_b32 v88, s65, v88, v88
	v_mul_f32_e32 v8, 0x3fb8aa3b, v8
	v_sub_f32_e32 v2, v2, v59
	v_mfma_f32_16x16x32_bf16 v[78:81], v[78:81], v[66:69], 0
	v_mul_f32_e32 v2, 0x3e000000, v2
	v_mul_f32_e32 v2, 0x3fb8aa3b, v2
	v_cvt_pk_bf16_f32 v27, v26, v27
	v_mfma_f32_16x16x32_bf16 v[66:69], v[82:85], v[66:69], 0
	v_cvt_pk_bf16_f32 v83, v63, v64
	v_cvt_pk_bf16_f32 v82, v61, v62
	ds_read2_b64 v[60:63], v0 offset0:72 offset1:76
	v_cvt_pk_bf16_f32 v85, v92, v53
	v_cvt_pk_bf16_f32 v84, v90, v91
	ds_read2_b64 v[90:93], v7 offset0:40 offset1:44
	v_cvt_pk_bf16_f32 v53, v52, v45
	s_waitcnt lgkmcnt(1)
	v_bfi_b32 v62, s65, v62, v62
	v_mfma_f32_16x16x32_bf16 v[70:73], v[86:89], v[82:85], v[70:73]
	ds_read2_b64 v[86:89], v20 offset0:104 offset1:108
	v_cvt_pk_bf16_f32 v52, v50, v51
	v_cvt_pk_bf16_f32 v51, v48, v49
	v_mfma_f32_16x16x32_bf16 v[60:63], v[60:63], v[82:85], v[78:81]
	v_cvt_pk_bf16_f32 v50, v46, v47
	ds_read2_b64 v[46:49], v0 offset0:80 offset1:84
	s_waitcnt lgkmcnt(2)
	v_bfi_b32 v92, s65, v92, v92
	ds_read2_b64 v[78:81], v21 offset0:16 offset1:20
	s_waitcnt lgkmcnt(2)
	v_bfi_b32 v88, s65, v88, v88
	v_mfma_f32_16x16x32_bf16 v[74:77], v[90:93], v[82:85], v[74:77]
	s_waitcnt lgkmcnt(0)
; __device__ __forceinline__ unsigned short f2bf(float f) { return (unsigned short)(pack2(f, 0.f) & 0xffffu); }
; __device__ void attn_item(const Params& p, int layer, int item, int dry) {
;     ...
;   sum += __shfl_xor(sum, 16);
;   sum += __shfl_xor(sum, 32);
;   const float inv = 1.f / sum;
;   f32x4 o[4] = {};
;   for (int ks = 0; ks < 8; ++ks) {
;     bf16x8 pb;
;     for (int j = 0; j < 4; ++j) {
;       pb[j] = (short)f2bf(s[2 * ks][j]);
;       pb[4 + j] = (short)f2bf(s[2 * ks + 1][j]);
;     }
;     for (int dt = 0; dt < 4; ++dt) {
;       const bf16_t* vp = Vt + (dt * 16 + r) * 264 + ks * 32 + quad * 4;
;       uint2 v0 = *(const uint2*)vp, v1 = *(const uint2*)(vp + 16);
;       bf16x8 av;
;       av[0] = (short)(v0.x & 0xffff); av[1] = (short)(v0.x >> 16); av[2] = (short)(v0.y & 0xffff); av[3] = (short)(v0.y >> 16);
;       av[4] = (short)(v1.x & 0xffff); av[5] = (short)(v1.x >> 16); av[6] = (short)(v1.y & 0xffff); av[7] = (short)(v1.y >> 16);
;       o[dt] = __builtin_amdgcn_mfma_f32_16x16x32_bf16(av, pb, o[dt], 0, 0, 0);
;     }
;   }
;   for (int dt = 0; dt < 4; ++dt) {
;     uint2 ov;
;     ov.x = pack2(o[dt][0] * inv, o[dt][1] * inv);
;     ov.y = pack2(o[dt][2] * inv, o[dt][3] * inv);
;     if (!dry) *(uint2*)(qp + dt * 16 + quad * 4) = ov;
;   }
	v_bfi_b32 v80, s65, v80, v80
	v_bfi_b32 v48, s65, v48, v48
	v_cvt_pk_bf16_f32 v45, v44, v37
	v_mfma_f32_16x16x32_bf16 v[64:67], v[86:89], v[82:85], v[66:69]
	ds_read2_b64 v[82:85], v7 offset0:48 offset1:52
	v_cvt_pk_bf16_f32 v44, v42, v43
	v_cvt_pk_bf16_f32 v43, v40, v41
	v_mfma_f32_16x16x32_bf16 v[68:71], v[78:81], v[50:53], v[70:73]
	ds_read2_b64 v[78:81], v20 offset0:112 offset1:116
	v_cvt_pk_bf16_f32 v42, v38, v39
	ds_read2_b64 v[38:41], v0 offset0:88 offset1:92
	v_mfma_f32_16x16x32_bf16 v[46:49], v[46:49], v[50:53], v[60:63]
	s_waitcnt lgkmcnt(2)
	v_bfi_b32 v84, s65, v84, v84
	s_waitcnt lgkmcnt(1)
	v_bfi_b32 v80, s65, v80, v80
	v_cvt_pk_bf16_f32 v37, v28, v36
	ds_read2_b64 v[60:63], v21 offset0:24 offset1:28
	s_waitcnt lgkmcnt(1)
	v_bfi_b32 v40, s65, v40, v40
	v_mfma_f32_16x16x32_bf16 v[72:75], v[82:85], v[50:53], v[74:77]
	v_cvt_pk_bf16_f32 v36, v34, v35
	v_cvt_pk_bf16_f32 v35, v32, v33
	s_waitcnt lgkmcnt(0)
	v_bfi_b32 v62, s65, v62, v62
	v_mfma_f32_16x16x32_bf16 v[50:53], v[78:81], v[50:53], v[64:67]
	v_cvt_pk_bf16_f32 v34, v30, v31
	ds_read2_b64 v[30:33], v0 offset0:96 offset1:100
	v_exp_f32_e32 v90, v8
	ds_read2_b64 v[64:67], v7 offset0:56 offset1:60
	v_mfma_f32_16x16x32_bf16 v[60:63], v[60:63], v[42:45], v[68:71]
	v_sub_f32_e32 v8, v9, v59
	s_waitcnt lgkmcnt(1)
	v_bfi_b32 v32, s65, v32, v32
	v_mul_f32_e32 v8, 0x3e000000, v8
	ds_read2_b64 v[68:71], v20 offset0:120 offset1:124
	v_mfma_f32_16x16x32_bf16 v[38:41], v[38:41], v[42:45], v[46:49]
	s_waitcnt lgkmcnt(1)
	v_bfi_b32 v66, s65, v66, v66
	v_mul_f32_e32 v8, 0x3fb8aa3b, v8
	v_exp_f32_e32 v9, v2
	ds_read2_b64 v[46:49], v21 offset0:32 offset1:36
	s_waitcnt lgkmcnt(1)
	v_bfi_b32 v70, s65, v70, v70
	v_mfma_f32_16x16x32_bf16 v[64:67], v[64:67], v[42:45], v[72:75]
	v_sub_f32_e32 v2, v3, v59
	v_exp_f32_e32 v76, v8
	s_waitcnt lgkmcnt(0)
	v_bfi_b32 v48, s65, v48, v48
	v_mfma_f32_16x16x32_bf16 v[42:45], v[68:71], v[42:45], v[50:53]
	v_mul_f32_e32 v2, 0x3e000000, v2
	v_mul_f32_e32 v2, 0x3fb8aa3b, v2
	v_exp_f32_e32 v28, v2
	ds_read2_b64 v[50:53], v7 offset0:64 offset1:68
	v_mfma_f32_16x16x32_bf16 v[46:49], v[46:49], v[34:37], v[60:63]
	v_add_f32_e32 v8, v90, v94
	v_add_f32_e32 v8, v76, v8
	v_add_f32_e32 v2, v9, v8
	ds_read2_b64 v[60:63], v20 offset0:128 offset1:132
	v_mfma_f32_16x16x32_bf16 v[30:33], v[30:33], v[34:37], v[38:41]
	s_waitcnt lgkmcnt(1)
	v_bfi_b32 v52, s65, v52, v52
	v_add_f32_e32 v8, v28, v2
	v_sub_f32_e32 v2, v4, v59
	ds_read2_b64 v[38:41], v21 offset0:40 offset1:44
	s_waitcnt lgkmcnt(1)
	v_bfi_b32 v62, s65, v62, v62
	v_mfma_f32_16x16x32_bf16 v[50:53], v[50:53], v[34:37], v[64:67]
	v_mul_f32_e32 v2, 0x3e000000, v2
	v_mul_f32_e32 v2, 0x3fb8aa3b, v2
	s_waitcnt lgkmcnt(0)
	v_bfi_b32 v40, s65, v40, v40
	v_mfma_f32_16x16x32_bf16 v[34:37], v[60:63], v[34:37], v[42:45]
	ds_read2_b64 v[60:63], v0 offset0:104 offset1:108
	v_cvt_pk_bf16_f32 v26, v18, v19
	v_cvt_pk_bf16_f32 v25, v24, v25
	v_cvt_pk_bf16_f32 v24, v22, v23
	v_exp_f32_e32 v18, v2
	v_sub_f32_e32 v19, v5, v59
	ds_read2_b64 v[2:5], v21 offset0:48 offset1:52
	ds_read2_b64 v[42:45], v7 offset0:72 offset1:76
	v_mfma_f32_16x16x32_bf16 v[38:41], v[38:41], v[24:27], v[46:49]
	v_cvt_pk_bf16_f32 v13, v12, v13
	v_cvt_pk_bf16_f32 v12, v10, v11
	v_cvt_pk_bf16_f32 v11, v16, v17
	ds_read2_b64 v[46:49], v20 offset0:136 offset1:140
	v_cvt_pk_bf16_f32 v10, v14, v15
	ds_read2_b64 v[14:17], v0 offset0:112 offset1:116
	s_waitcnt lgkmcnt(4)
	v_bfi_b32 v62, s65, v62, v62
	s_waitcnt lgkmcnt(3)
	v_bfi_b32 v4, s65, v4, v4
	s_waitcnt lgkmcnt(2)
	v_bfi_b32 v44, s65, v44, v44
	s_waitcnt lgkmcnt(1)
	v_bfi_b32 v48, s65, v48, v48
	s_waitcnt lgkmcnt(0)
	v_bfi_b32 v16, s65, v16, v16
	v_mfma_f32_16x16x32_bf16 v[30:33], v[60:63], v[24:27], v[30:33]
	v_mul_f32_e32 v19, 0x3e000000, v19
	v_mul_f32_e32 v19, 0x3fb8aa3b, v19
	v_exp_f32_e32 v19, v19
	v_mfma_f32_16x16x32_bf16 v[2:5], v[2:5], v[10:13], v[38:41]
	v_add_f32_e32 v8, v18, v8
	s_nop 1
	ds_read2_b64 v[38:41], v20 offset0:144 offset1:148
	v_mfma_f32_16x16x32_bf16 v[42:45], v[42:45], v[24:27], v[50:53]
	s_waitcnt lgkmcnt(0)
	v_bfi_b32 v40, s65, v40, v40
	v_mfma_f32_16x16x32_bf16 v[22:25], v[46:49], v[24:27], v[34:37]
	s_nop 2
	ds_read2_b64 v[34:37], v7 offset0:80 offset1:84
	v_mfma_f32_16x16x32_bf16 v[14:17], v[14:17], v[10:13], v[30:33]
	s_waitcnt lgkmcnt(0)
	v_bfi_b32 v36, s65, v36, v36
	s_nop 0
	ds_read2_b64 v[30:33], v21 offset0:56 offset1:60
	v_mfma_f32_16x16x32_bf16 v[22:25], v[38:41], v[10:13], v[22:25]
	v_cvt_pk_bf16_f32 v41, v18, v19
	v_cvt_pk_bf16_f32 v40, v9, v28
	v_cvt_pk_bf16_f32 v39, v90, v76
	s_waitcnt lgkmcnt(0)
	v_bfi_b32 v32, s65, v32, v32
	v_cvt_pk_bf16_f32 v38, v6, v29
	v_mfma_f32_16x16x32_bf16 v[34:37], v[34:37], v[10:13], v[42:45]
	v_add_f32_e32 v21, v19, v8
	ds_read2_b64 v[8:11], v7 offset0:88 offset1:92
	ds_read2_b64 v[26:29], v0 offset0:120 offset1:124
	v_mfma_f32_16x16x32_bf16 v[2:5], v[30:33], v[38:41], v[2:5]
	ds_read2_b64 v[30:33], v20 offset0:152 offset1:156
	ds_bpermute_b32 v0, v58, v21
	s_waitcnt lgkmcnt(3)
	v_bfi_b32 v10, s65, v10, v10
	s_waitcnt lgkmcnt(2)
	v_bfi_b32 v28, s65, v28, v28
	s_waitcnt lgkmcnt(1)
	v_bfi_b32 v32, s65, v32, v32
	s_waitcnt lgkmcnt(0)
	v_add_f32_e32 v0, v21, v0
	ds_bpermute_b32 v18, v57, v0
	v_mfma_f32_16x16x32_bf16 v[6:9], v[8:11], v[38:41], v[34:37]
	v_mfma_f32_16x16x32_bf16 v[10:13], v[26:29], v[38:41], v[14:17]
	v_mfma_f32_16x16x32_bf16 v[14:17], v[30:33], v[38:41], v[22:25]
	s_cbranch_vccnz .LBB0_1351
	s_waitcnt lgkmcnt(0)
	v_add_f32_e32 v0, v0, v18
	v_div_scale_f32 v18, s[4:5], v0, v0, 1.0
	v_rcp_f32_e32 v19, v18
	v_mov_b32_e32 v57, v1
	v_lshl_add_u64 v[20:21], v[54:55], 0, v[56:57]
	v_fma_f32 v22, -v18, v19, 1.0
	v_fmac_f32_e32 v19, v22, v19
	v_div_scale_f32 v22, vcc, 1.0, v0, 1.0
	v_mul_f32_e32 v23, v22, v19
	v_fma_f32 v24, -v18, v23, v22
	v_fmac_f32_e32 v23, v24, v19
	v_fma_f32 v18, -v18, v23, v22
	v_div_fmas_f32 v18, v18, v19, v23
	v_div_fixup_f32 v0, v18, v0, 1.0
	v_pk_mul_f32 v[4:5], v[0:1], v[4:5] op_sel_hi:[0,1]
	v_pk_mul_f32 v[2:3], v[0:1], v[2:3] op_sel_hi:[0,1]
	v_cvt_pk_bf16_f32 v5, v4, v5
	v_cvt_pk_bf16_f32 v4, v2, v3
	global_store_dwordx2 v[20:21], v[4:5], off
	v_pk_mul_f32 v[2:3], v[0:1], v[8:9] op_sel_hi:[0,1]
	v_pk_mul_f32 v[4:5], v[0:1], v[6:7] op_sel_hi:[0,1]
	v_cvt_pk_bf16_f32 v3, v2, v3
	v_cvt_pk_bf16_f32 v2, v4, v5
	global_store_dwordx2 v[20:21], v[2:3], off offset:32
	v_pk_mul_f32 v[2:3], v[0:1], v[12:13] op_sel_hi:[0,1]
	v_pk_mul_f32 v[4:5], v[0:1], v[10:11] op_sel_hi:[0,1]
	v_cvt_pk_bf16_f32 v3, v2, v3
	v_cvt_pk_bf16_f32 v2, v4, v5
	global_store_dwordx2 v[20:21], v[2:3], off offset:64
	v_pk_mul_f32 v[2:3], v[0:1], v[16:17] op_sel_hi:[0,1]
	v_pk_mul_f32 v[4:5], v[0:1], v[14:15] op_sel_hi:[0,1]
	v_cvt_pk_bf16_f32 v3, v2, v3
	v_cvt_pk_bf16_f32 v2, v4, v5
	global_store_dwordx2 v[20:21], v[2:3], off offset:96
